# PEER token tail: wave-wide sum of squares via DPP permutes and v_permlane16/32_swap instead of the ds_bpermute butterfly (on top of v66)
# baseline (speedup 1.0000x reference)
.LBB0_900:
	s_waitcnt vmcnt(34)
	v_pk_fma_f32 v[16:17], v[16:17], v[208:209], v[0:1]
	v_add_u32_e32 v0, 5, v144
	v_mad_u64_u32 v[44:45], s[10:11], v0, s27, v[108:109]
	v_pk_fma_f32 v[12:13], v[28:29], v[200:201], v[12:13]
	v_pk_fma_f32 v[14:15], v[30:31], v[218:219], v[14:15]
	s_waitcnt vmcnt(32)
	v_pk_fma_f32 v[24:25], v[24:25], v[216:217], v[8:9]
	v_pk_fma_f32 v[26:27], v[26:27], v[214:215], v[10:11]
	v_pk_fma_f32 v[8:9], v[20:21], v[212:213], v[4:5]
	v_pk_fma_f32 v[10:11], v[22:23], v[210:211], v[6:7]
	v_pk_fma_f32 v[18:19], v[18:19], v[206:207], v[2:3]
	v_add_co_u32_e32 v46, vcc, s57, v44
	global_store_dwordx4 v[162:163], v[12:15], off
	global_store_dwordx4 v[162:163], v[24:27], off offset:16
	global_store_dwordx4 v[162:163], v[8:11], off offset:32
	global_store_dwordx4 v[162:163], v[16:19], off offset:48
	v_addc_co_u32_e32 v47, vcc, 0, v45, vcc
	global_load_dwordx4 v[0:3], v[106:107], off offset:16
	global_load_dwordx4 v[4:7], v[106:107], off
	global_load_dwordx4 v[20:23], v[46:47], off
	v_lshl_add_u64 v[28:29], v[44:45], 0, s[16:17]
	global_load_dwordx4 v[28:31], v[28:29], off offset:16
	s_nop 0
	global_load_dwordx4 v[32:35], v[44:45], off offset:16
	global_load_dwordx4 v[36:39], v[44:45], off
	v_mov_b32_e32 v60, v0
	v_mov_b32_e32 v61, v1
	global_load_dwordx4 v[202:205], v[106:107], off offset:32
	global_load_dwordx4 v[196:199], v[46:47], off offset:32
	global_load_dwordx4 v[192:195], v[106:107], off offset:48
	v_lshl_add_u64 v[60:61], v[44:45], 0, s[22:23]
	global_load_dwordx4 v[188:191], v[60:61], off offset:16
	global_load_dwordx4 v[184:187], v[44:45], off offset:32
	global_load_dwordx4 v[180:183], v[44:45], off offset:48
	v_pk_mul_f32 v[40:41], v[12:13], v[12:13]
	v_pk_mul_f32 v[42:43], v[14:15], v[14:15]
	v_add_f32_e32 v40, v40, v41
	v_add_f32_e32 v40, v40, v42
	v_pk_mul_f32 v[48:49], v[24:25], v[24:25]
	v_add_f32_e32 v40, v43, v40
	v_add_f32_e32 v40, v48, v40
	v_pk_mul_f32 v[50:51], v[26:27], v[26:27]
	v_add_f32_e32 v40, v49, v40
	v_add_f32_e32 v40, v50, v40
	v_pk_mul_f32 v[52:53], v[8:9], v[8:9]
	v_add_f32_e32 v40, v51, v40
	v_add_f32_e32 v40, v52, v40
	v_pk_mul_f32 v[54:55], v[10:11], v[10:11]
	v_add_f32_e32 v40, v53, v40
	v_add_f32_e32 v40, v54, v40
	v_pk_mul_f32 v[56:57], v[16:17], v[16:17]
	v_add_f32_e32 v40, v55, v40
	v_add_f32_e32 v40, v56, v40
	v_pk_mul_f32 v[58:59], v[18:19], v[18:19]
	v_add_f32_e32 v40, v57, v40
	v_add_f32_e32 v40, v58, v40
	v_add_f32_e32 v40, v59, v40
	v_accvgpr_read_b32 v41, a71
	s_nop 1
	v_add_f32_dpp v40, v40, v40 quad_perm:[1,0,3,2] row_mask:0xf bank_mask:0xf bound_ctrl:1
	s_nop 1
	v_add_f32_dpp v40, v40, v40 quad_perm:[2,3,0,1] row_mask:0xf bank_mask:0xf bound_ctrl:1
	s_nop 1
	v_add_f32_dpp v40, v40, v40 row_half_mirror row_mask:0xf bank_mask:0xf bound_ctrl:1
	s_nop 1
	v_add_f32_dpp v40, v40, v40 row_mirror row_mask:0xf bank_mask:0xf bound_ctrl:1
	v_mov_b32_e32 v41, v40
	s_nop 1
	v_permlane16_swap_b32_e32 v41, v40
	s_nop 1
	v_add_f32_e32 v40, v41, v40
	v_mov_b32_e32 v41, v40
	s_nop 1
	v_permlane32_swap_b32_e32 v41, v40
	s_nop 1
	v_add_f32_e32 v40, v41, v40
	v_mov_b32_e32 v42, 0x358637bd
	v_mov_b32_e32 v102, v118
	v_mov_b32_e32 v116, v120
	s_waitcnt vmcnt(19)
	v_accvgpr_read_b32 v142, a68
	v_accvgpr_read_b32 v41, a74
	s_waitcnt vmcnt(18)
	v_accvgpr_read_b32 v143, a69
	v_accvgpr_read_b32 v41, a75
	v_fmamk_f32 v40, v40, 0x3a800000, v42
	v_mul_f32_e32 v41, 0x4b800000, v40
	v_cmp_gt_f32_e32 vcc, s56, v40
	s_nop 1
	v_cndmask_b32_e32 v40, v40, v41, vcc
	v_rsq_f32_e32 v42, v40
	v_lshl_add_u64 v[40:41], v[122:123], 1, v[104:105]
	v_mul_f32_e32 v43, 0x45800000, v42
	v_cndmask_b32_e32 v42, v42, v43, vcc
	v_pk_mul_f32 v[12:13], v[12:13], v[42:43] op_sel_hi:[1,0]
	v_pk_mul_f32 v[14:15], v[14:15], v[42:43] op_sel_hi:[1,0]
	v_pk_mul_f32 v[24:25], v[24:25], v[42:43] op_sel_hi:[1,0]
	v_pk_mul_f32 v[26:27], v[26:27], v[42:43] op_sel_hi:[1,0]
	s_waitcnt vmcnt(10)
	v_pk_mul_f32 v[4:5], v[4:5], v[12:13]
	v_pk_mul_f32 v[6:7], v[6:7], v[14:15]
	v_pk_mul_f32 v[0:1], v[24:25], v[0:1]
	v_pk_mul_f32 v[2:3], v[26:27], v[2:3]
	s_waitcnt vmcnt(9)
	v_pk_add_f32 v[12:13], v[20:21], 1.0 op_sel_hi:[1,0]
	v_pk_add_f32 v[14:15], v[22:23], 1.0 op_sel_hi:[1,0]
	s_waitcnt vmcnt(8)
	v_pk_add_f32 v[20:21], v[28:29], 1.0 op_sel_hi:[1,0]
	v_pk_add_f32 v[22:23], v[30:31], 1.0 op_sel_hi:[1,0]
	s_waitcnt vmcnt(6)
	v_pk_fma_f32 v[4:5], v[12:13], v[4:5], v[36:37]
	v_pk_fma_f32 v[6:7], v[6:7], v[14:15], v[38:39]
	v_pk_fma_f32 v[12:13], v[0:1], v[20:21], v[32:33]
	v_pk_fma_f32 v[14:15], v[2:3], v[22:23], v[34:35]
	v_cvt_pk_bf16_f32 v0, v4, v5
	v_cvt_pk_bf16_f32 v1, v6, v7
	v_cvt_pk_bf16_f32 v2, v12, v13
	v_cvt_pk_bf16_f32 v3, v14, v15
	global_store_dwordx4 v[40:41], v[0:3], off
	s_waitcnt vmcnt(6)
	s_nop 1
	v_mov_b64_e32 v[12:13], v[202:203]
	v_mov_b64_e32 v[14:15], v[204:205]
	s_waitcnt vmcnt(5)
	s_nop 1
	v_mov_b64_e32 v[20:21], v[196:197]
	v_mov_b64_e32 v[22:23], v[198:199]
	s_waitcnt vmcnt(4)
	s_nop 1
	v_mov_b64_e32 v[24:25], v[192:193]
	v_mov_b64_e32 v[26:27], v[194:195]
	v_lshl_add_u64 v[0:1], v[44:45], 0, s[22:23]
	s_waitcnt vmcnt(3)
	s_nop 1
	v_mov_b64_e32 v[28:29], v[188:189]
	v_mov_b64_e32 v[30:31], v[190:191]
	s_waitcnt vmcnt(2)
	s_nop 1
	v_mov_b64_e32 v[32:33], v[184:185]
	v_mov_b64_e32 v[34:35], v[186:187]
	s_waitcnt vmcnt(1)
	s_nop 1
	v_mov_b64_e32 v[36:37], v[180:181]
	v_mov_b64_e32 v[38:39], v[182:183]
	v_pk_mul_f32 v[8:9], v[8:9], v[42:43] op_sel_hi:[1,0]
	v_pk_mul_f32 v[10:11], v[10:11], v[42:43] op_sel_hi:[1,0]
	v_pk_mul_f32 v[16:17], v[16:17], v[42:43] op_sel_hi:[1,0]
	v_pk_mul_f32 v[18:19], v[18:19], v[42:43] op_sel_hi:[1,0]
	v_cmp_lt_i32_e32 vcc, s31, v128
	v_accvgpr_read_b32 v4, a36
	v_accvgpr_read_b32 v0, a32
	v_accvgpr_read_b32 v5, a37
	v_accvgpr_read_b32 v6, a38
	v_accvgpr_read_b32 v7, a39
	v_accvgpr_read_b32 v1, a33
	v_accvgpr_read_b32 v2, a34
	v_accvgpr_read_b32 v3, a35
	s_or_b64 s[18:19], vcc, s[18:19]
	v_pk_mul_f32 v[8:9], v[8:9], v[12:13]
	v_pk_add_f32 v[12:13], v[20:21], 1.0 op_sel_hi:[1,0]
	v_pk_mul_f32 v[10:11], v[10:11], v[14:15]
	v_pk_add_f32 v[14:15], v[22:23], 1.0 op_sel_hi:[1,0]
	v_pk_mul_f32 v[16:17], v[16:17], v[24:25]
	v_pk_add_f32 v[20:21], v[28:29], 1.0 op_sel_hi:[1,0]
	v_pk_mul_f32 v[18:19], v[18:19], v[26:27]
	v_pk_add_f32 v[22:23], v[30:31], 1.0 op_sel_hi:[1,0]
	v_pk_fma_f32 v[8:9], v[8:9], v[12:13], v[32:33]
	v_pk_fma_f32 v[10:11], v[10:11], v[14:15], v[34:35]
	v_pk_fma_f32 v[12:13], v[16:17], v[20:21], v[36:37]
	v_pk_fma_f32 v[14:15], v[18:19], v[22:23], v[38:39]
	v_cvt_pk_bf16_f32 v8, v8, v9
	v_cvt_pk_bf16_f32 v9, v10, v11
	v_cvt_pk_bf16_f32 v10, v12, v13
	v_cvt_pk_bf16_f32 v11, v14, v15
	global_store_dwordx4 v[40:41], v[8:11], off offset:16
	s_andn2_b64 exec, exec, s[18:19]
	s_cbranch_execz .LBB0_922

.LBB0_1385:
	s_waitcnt vmcnt(34)
	v_pk_fma_f32 v[16:17], v[16:17], v[208:209], v[0:1]
	v_add_u32_e32 v0, 10, v144
	v_mad_u64_u32 v[44:45], s[12:13], v0, s27, v[108:109]
	v_pk_fma_f32 v[12:13], v[28:29], v[200:201], v[12:13]
	v_pk_fma_f32 v[14:15], v[30:31], v[218:219], v[14:15]
	s_waitcnt vmcnt(32)
	v_pk_fma_f32 v[24:25], v[24:25], v[216:217], v[8:9]
	v_pk_fma_f32 v[26:27], v[26:27], v[214:215], v[10:11]
	v_pk_fma_f32 v[8:9], v[20:21], v[212:213], v[4:5]
	v_pk_fma_f32 v[10:11], v[22:23], v[210:211], v[6:7]
	v_pk_fma_f32 v[18:19], v[18:19], v[206:207], v[2:3]
	v_add_co_u32_e32 v46, vcc, s57, v44
	global_store_dwordx4 v[162:163], v[12:15], off
	global_store_dwordx4 v[162:163], v[24:27], off offset:16
	global_store_dwordx4 v[162:163], v[8:11], off offset:32
	global_store_dwordx4 v[162:163], v[16:19], off offset:48
	v_addc_co_u32_e32 v47, vcc, 0, v45, vcc
	global_load_dwordx4 v[0:3], v[106:107], off offset:16
	global_load_dwordx4 v[4:7], v[106:107], off
	global_load_dwordx4 v[20:23], v[46:47], off
	v_lshl_add_u64 v[28:29], v[44:45], 0, s[20:21]
	global_load_dwordx4 v[28:31], v[28:29], off offset:16
	s_nop 0
	global_load_dwordx4 v[32:35], v[44:45], off offset:16
	global_load_dwordx4 v[36:39], v[44:45], off
	v_mov_b32_e32 v60, v0
	v_mov_b32_e32 v61, v1
	global_load_dwordx4 v[202:205], v[106:107], off offset:32
	global_load_dwordx4 v[196:199], v[46:47], off offset:32
	global_load_dwordx4 v[192:195], v[106:107], off offset:48
	v_lshl_add_u64 v[60:61], v[44:45], 0, s[22:23]
	global_load_dwordx4 v[188:191], v[60:61], off offset:16
	global_load_dwordx4 v[184:187], v[44:45], off offset:32
	global_load_dwordx4 v[180:183], v[44:45], off offset:48
	v_pk_mul_f32 v[40:41], v[12:13], v[12:13]
	v_pk_mul_f32 v[42:43], v[14:15], v[14:15]
	v_add_f32_e32 v40, v40, v41
	v_add_f32_e32 v40, v40, v42
	v_pk_mul_f32 v[48:49], v[24:25], v[24:25]
	v_add_f32_e32 v40, v43, v40
	v_add_f32_e32 v40, v48, v40
	v_pk_mul_f32 v[50:51], v[26:27], v[26:27]
	v_add_f32_e32 v40, v49, v40
	v_add_f32_e32 v40, v50, v40
	v_pk_mul_f32 v[52:53], v[8:9], v[8:9]
	v_add_f32_e32 v40, v51, v40
	v_add_f32_e32 v40, v52, v40
	v_pk_mul_f32 v[54:55], v[10:11], v[10:11]
	v_add_f32_e32 v40, v53, v40
	v_add_f32_e32 v40, v54, v40
	v_pk_mul_f32 v[56:57], v[16:17], v[16:17]
	v_add_f32_e32 v40, v55, v40
	v_add_f32_e32 v40, v56, v40
	v_pk_mul_f32 v[58:59], v[18:19], v[18:19]
	v_add_f32_e32 v40, v57, v40
	v_add_f32_e32 v40, v58, v40
	v_add_f32_e32 v40, v59, v40
	v_accvgpr_read_b32 v41, a71
	s_nop 1
	v_add_f32_dpp v40, v40, v40 quad_perm:[1,0,3,2] row_mask:0xf bank_mask:0xf bound_ctrl:1
	s_nop 1
	v_add_f32_dpp v40, v40, v40 quad_perm:[2,3,0,1] row_mask:0xf bank_mask:0xf bound_ctrl:1
	s_nop 1
	v_add_f32_dpp v40, v40, v40 row_half_mirror row_mask:0xf bank_mask:0xf bound_ctrl:1
	s_nop 1
	v_add_f32_dpp v40, v40, v40 row_mirror row_mask:0xf bank_mask:0xf bound_ctrl:1
	v_mov_b32_e32 v41, v40
	s_nop 1
	v_permlane16_swap_b32_e32 v41, v40
	s_nop 1
	v_add_f32_e32 v40, v41, v40
	v_mov_b32_e32 v41, v40
	s_nop 1
	v_permlane32_swap_b32_e32 v41, v40
	s_nop 1
	v_add_f32_e32 v40, v41, v40
	v_mov_b32_e32 v42, 0x358637bd
	v_mov_b32_e32 v104, v118
	v_mov_b32_e32 v116, v120
	s_waitcnt vmcnt(19)
	v_accvgpr_read_b32 v142, a68
	v_accvgpr_read_b32 v41, a74
	s_waitcnt vmcnt(18)
	v_accvgpr_read_b32 v143, a69
	v_accvgpr_read_b32 v41, a75
	v_fmamk_f32 v40, v40, 0x3a800000, v42
	v_mul_f32_e32 v41, 0x4b800000, v40
	v_cmp_gt_f32_e32 vcc, s56, v40
	s_nop 1
	v_cndmask_b32_e32 v40, v40, v41, vcc
	v_rsq_f32_e32 v42, v40
	v_lshl_add_u64 v[40:41], v[122:123], 1, v[102:103]
	v_mul_f32_e32 v43, 0x45800000, v42
	v_cndmask_b32_e32 v42, v42, v43, vcc
	v_pk_mul_f32 v[12:13], v[12:13], v[42:43] op_sel_hi:[1,0]
	v_pk_mul_f32 v[14:15], v[14:15], v[42:43] op_sel_hi:[1,0]
	v_pk_mul_f32 v[24:25], v[24:25], v[42:43] op_sel_hi:[1,0]
	v_pk_mul_f32 v[26:27], v[26:27], v[42:43] op_sel_hi:[1,0]
	s_waitcnt vmcnt(10)
	v_pk_mul_f32 v[4:5], v[4:5], v[12:13]
	v_pk_mul_f32 v[6:7], v[6:7], v[14:15]
	v_pk_mul_f32 v[0:1], v[24:25], v[0:1]
	v_pk_mul_f32 v[2:3], v[26:27], v[2:3]
	s_waitcnt vmcnt(9)
	v_pk_add_f32 v[12:13], v[20:21], 1.0 op_sel_hi:[1,0]
	v_pk_add_f32 v[14:15], v[22:23], 1.0 op_sel_hi:[1,0]
	s_waitcnt vmcnt(8)
	v_pk_add_f32 v[20:21], v[28:29], 1.0 op_sel_hi:[1,0]
	v_pk_add_f32 v[22:23], v[30:31], 1.0 op_sel_hi:[1,0]
	s_waitcnt vmcnt(6)
	v_pk_fma_f32 v[4:5], v[12:13], v[4:5], v[36:37]
	v_pk_fma_f32 v[6:7], v[6:7], v[14:15], v[38:39]
	v_pk_fma_f32 v[12:13], v[0:1], v[20:21], v[32:33]
	v_pk_fma_f32 v[14:15], v[2:3], v[22:23], v[34:35]
	v_cvt_pk_bf16_f32 v0, v4, v5
	v_cvt_pk_bf16_f32 v1, v6, v7
	v_cvt_pk_bf16_f32 v2, v12, v13
	v_cvt_pk_bf16_f32 v3, v14, v15
	global_store_dwordx4 v[40:41], v[0:3], off
	s_waitcnt vmcnt(6)
	s_nop 1
	v_mov_b64_e32 v[12:13], v[202:203]
	v_mov_b64_e32 v[14:15], v[204:205]
	s_waitcnt vmcnt(5)
	s_nop 1
	v_mov_b64_e32 v[20:21], v[196:197]
	v_mov_b64_e32 v[22:23], v[198:199]
	s_waitcnt vmcnt(4)
	s_nop 1
	v_mov_b64_e32 v[24:25], v[192:193]
	v_mov_b64_e32 v[26:27], v[194:195]
	v_lshl_add_u64 v[0:1], v[44:45], 0, s[22:23]
	s_waitcnt vmcnt(3)
	s_nop 1
	v_mov_b64_e32 v[28:29], v[188:189]
	v_mov_b64_e32 v[30:31], v[190:191]
	s_waitcnt vmcnt(2)
	s_nop 1
	v_mov_b64_e32 v[32:33], v[184:185]
	v_mov_b64_e32 v[34:35], v[186:187]
	s_waitcnt vmcnt(1)
	s_nop 1
	v_mov_b64_e32 v[36:37], v[180:181]
	v_mov_b64_e32 v[38:39], v[182:183]
	v_pk_mul_f32 v[8:9], v[8:9], v[42:43] op_sel_hi:[1,0]
	v_pk_mul_f32 v[10:11], v[10:11], v[42:43] op_sel_hi:[1,0]
	v_pk_mul_f32 v[16:17], v[16:17], v[42:43] op_sel_hi:[1,0]
	v_pk_mul_f32 v[18:19], v[18:19], v[42:43] op_sel_hi:[1,0]
	v_cmp_lt_i32_e32 vcc, s31, v128
	v_accvgpr_read_b32 v4, a36
	v_accvgpr_read_b32 v0, a32
	v_accvgpr_read_b32 v5, a37
	v_accvgpr_read_b32 v6, a38
	v_accvgpr_read_b32 v7, a39
	v_accvgpr_read_b32 v1, a33
	v_accvgpr_read_b32 v2, a34
	v_accvgpr_read_b32 v3, a35
	s_or_b64 s[18:19], vcc, s[18:19]
	v_pk_mul_f32 v[8:9], v[8:9], v[12:13]
	v_pk_add_f32 v[12:13], v[20:21], 1.0 op_sel_hi:[1,0]
	v_pk_mul_f32 v[10:11], v[10:11], v[14:15]
	v_pk_add_f32 v[14:15], v[22:23], 1.0 op_sel_hi:[1,0]
	v_pk_mul_f32 v[16:17], v[16:17], v[24:25]
	v_pk_add_f32 v[20:21], v[28:29], 1.0 op_sel_hi:[1,0]
	v_pk_mul_f32 v[18:19], v[18:19], v[26:27]
	v_pk_add_f32 v[22:23], v[30:31], 1.0 op_sel_hi:[1,0]
	v_pk_fma_f32 v[8:9], v[8:9], v[12:13], v[32:33]
	v_pk_fma_f32 v[10:11], v[10:11], v[14:15], v[34:35]
	v_pk_fma_f32 v[12:13], v[16:17], v[20:21], v[36:37]
	v_pk_fma_f32 v[14:15], v[18:19], v[22:23], v[38:39]
	v_cvt_pk_bf16_f32 v8, v8, v9
	v_cvt_pk_bf16_f32 v9, v10, v11
	v_cvt_pk_bf16_f32 v10, v12, v13
	v_cvt_pk_bf16_f32 v11, v14, v15
	global_store_dwordx4 v[40:41], v[8:11], off offset:16
	s_andn2_b64 exec, exec, s[18:19]
	s_cbranch_execz .LBB0_1407

.LBB0_2084:
	s_waitcnt vmcnt(34)
	v_pk_fma_f32 v[16:17], v[16:17], v[206:207], v[0:1]
	v_add_u32_e32 v0, 15, v144
	v_mad_u64_u32 v[44:45], s[12:13], v0, s27, v[108:109]
	v_pk_fma_f32 v[12:13], v[28:29], v[198:199], v[12:13]
	v_pk_fma_f32 v[14:15], v[30:31], v[216:217], v[14:15]
	s_waitcnt vmcnt(32)
	v_pk_fma_f32 v[24:25], v[24:25], v[214:215], v[8:9]
	v_pk_fma_f32 v[26:27], v[26:27], v[212:213], v[10:11]
	v_pk_fma_f32 v[8:9], v[20:21], v[210:211], v[4:5]
	v_pk_fma_f32 v[10:11], v[22:23], v[208:209], v[6:7]
	v_pk_fma_f32 v[18:19], v[18:19], v[204:205], v[2:3]
	v_add_co_u32_e32 v46, vcc, s57, v44
	global_store_dwordx4 v[160:161], v[12:15], off
	global_store_dwordx4 v[160:161], v[24:27], off offset:16
	global_store_dwordx4 v[160:161], v[8:11], off offset:32
	global_store_dwordx4 v[160:161], v[16:19], off offset:48
	v_addc_co_u32_e32 v47, vcc, 0, v45, vcc
	global_load_dwordx4 v[0:3], v[106:107], off offset:16
	global_load_dwordx4 v[4:7], v[106:107], off
	global_load_dwordx4 v[20:23], v[46:47], off
	v_lshl_add_u64 v[28:29], v[44:45], 0, s[20:21]
	global_load_dwordx4 v[28:31], v[28:29], off offset:16
	s_nop 0
	global_load_dwordx4 v[32:35], v[44:45], off offset:16
	global_load_dwordx4 v[36:39], v[44:45], off
	v_mov_b32_e32 v60, v0
	v_mov_b32_e32 v61, v1
	global_load_dwordx4 v[200:203], v[106:107], off offset:32
	global_load_dwordx4 v[194:197], v[46:47], off offset:32
	global_load_dwordx4 v[190:193], v[106:107], off offset:48
	v_lshl_add_u64 v[60:61], v[44:45], 0, s[22:23]
	global_load_dwordx4 v[186:189], v[60:61], off offset:16
	global_load_dwordx4 v[182:185], v[44:45], off offset:32
	global_load_dwordx4 v[178:181], v[44:45], off offset:48
	v_pk_mul_f32 v[40:41], v[12:13], v[12:13]
	v_pk_mul_f32 v[42:43], v[14:15], v[14:15]
	v_add_f32_e32 v40, v40, v41
	v_add_f32_e32 v40, v40, v42
	v_pk_mul_f32 v[48:49], v[24:25], v[24:25]
	v_add_f32_e32 v40, v43, v40
	v_add_f32_e32 v40, v48, v40
	v_pk_mul_f32 v[50:51], v[26:27], v[26:27]
	v_add_f32_e32 v40, v49, v40
	v_add_f32_e32 v40, v50, v40
	v_pk_mul_f32 v[52:53], v[8:9], v[8:9]
	v_add_f32_e32 v40, v51, v40
	v_add_f32_e32 v40, v52, v40
	v_pk_mul_f32 v[54:55], v[10:11], v[10:11]
	v_add_f32_e32 v40, v53, v40
	v_add_f32_e32 v40, v54, v40
	v_pk_mul_f32 v[56:57], v[16:17], v[16:17]
	v_add_f32_e32 v40, v55, v40
	v_add_f32_e32 v40, v56, v40
	v_pk_mul_f32 v[58:59], v[18:19], v[18:19]
	v_add_f32_e32 v40, v57, v40
	v_add_f32_e32 v40, v58, v40
	v_add_f32_e32 v40, v59, v40
	v_accvgpr_read_b32 v41, a71
	s_nop 1
	v_add_f32_dpp v40, v40, v40 quad_perm:[1,0,3,2] row_mask:0xf bank_mask:0xf bound_ctrl:1
	s_nop 1
	v_add_f32_dpp v40, v40, v40 quad_perm:[2,3,0,1] row_mask:0xf bank_mask:0xf bound_ctrl:1
	s_nop 1
	v_add_f32_dpp v40, v40, v40 row_half_mirror row_mask:0xf bank_mask:0xf bound_ctrl:1
	s_nop 1
	v_add_f32_dpp v40, v40, v40 row_mirror row_mask:0xf bank_mask:0xf bound_ctrl:1
	v_mov_b32_e32 v41, v40
	s_nop 1
	v_permlane16_swap_b32_e32 v41, v40
	s_nop 1
	v_add_f32_e32 v40, v41, v40
	v_mov_b32_e32 v41, v40
	s_nop 1
	v_permlane32_swap_b32_e32 v41, v40
	s_nop 1
	v_add_f32_e32 v40, v41, v40
	v_mov_b32_e32 v42, 0x358637bd
	v_mov_b32_e32 v102, v118
	v_mov_b32_e32 v116, v120
	s_waitcnt vmcnt(19)
	v_accvgpr_read_b32 v142, a68
	v_accvgpr_read_b32 v41, a74
	s_waitcnt vmcnt(18)
	v_accvgpr_read_b32 v143, a69
	v_accvgpr_read_b32 v41, a75
	v_fmamk_f32 v40, v40, 0x3a800000, v42
	v_mul_f32_e32 v41, 0x4b800000, v40
	v_cmp_gt_f32_e32 vcc, s56, v40
	s_nop 1
	v_cndmask_b32_e32 v40, v40, v41, vcc
	v_rsq_f32_e32 v42, v40
	v_lshl_add_u64 v[40:41], v[122:123], 1, v[104:105]
	v_mul_f32_e32 v43, 0x45800000, v42
	v_cndmask_b32_e32 v42, v42, v43, vcc
	v_pk_mul_f32 v[12:13], v[12:13], v[42:43] op_sel_hi:[1,0]
	v_pk_mul_f32 v[14:15], v[14:15], v[42:43] op_sel_hi:[1,0]
	v_pk_mul_f32 v[24:25], v[24:25], v[42:43] op_sel_hi:[1,0]
	v_pk_mul_f32 v[26:27], v[26:27], v[42:43] op_sel_hi:[1,0]
	s_waitcnt vmcnt(10)
	v_pk_mul_f32 v[4:5], v[4:5], v[12:13]
	v_pk_mul_f32 v[6:7], v[6:7], v[14:15]
	v_pk_mul_f32 v[0:1], v[24:25], v[0:1]
	v_pk_mul_f32 v[2:3], v[26:27], v[2:3]
	s_waitcnt vmcnt(9)
	v_pk_add_f32 v[12:13], v[20:21], 1.0 op_sel_hi:[1,0]
	v_pk_add_f32 v[14:15], v[22:23], 1.0 op_sel_hi:[1,0]
	s_waitcnt vmcnt(8)
	v_pk_add_f32 v[20:21], v[28:29], 1.0 op_sel_hi:[1,0]
	v_pk_add_f32 v[22:23], v[30:31], 1.0 op_sel_hi:[1,0]
	s_waitcnt vmcnt(6)
	v_pk_fma_f32 v[4:5], v[12:13], v[4:5], v[36:37]
	v_pk_fma_f32 v[6:7], v[6:7], v[14:15], v[38:39]
	v_pk_fma_f32 v[12:13], v[0:1], v[20:21], v[32:33]
	v_pk_fma_f32 v[14:15], v[2:3], v[22:23], v[34:35]
	v_cvt_pk_bf16_f32 v0, v4, v5
	v_cvt_pk_bf16_f32 v1, v6, v7
	v_cvt_pk_bf16_f32 v2, v12, v13
	v_cvt_pk_bf16_f32 v3, v14, v15
	global_store_dwordx4 v[40:41], v[0:3], off
	s_waitcnt vmcnt(6)
	s_nop 1
	v_mov_b64_e32 v[12:13], v[200:201]
	v_mov_b64_e32 v[14:15], v[202:203]
	s_waitcnt vmcnt(5)
	s_nop 1
	v_mov_b64_e32 v[20:21], v[194:195]
	v_mov_b64_e32 v[22:23], v[196:197]
	s_waitcnt vmcnt(4)
	s_nop 1
	v_mov_b64_e32 v[24:25], v[190:191]
	v_mov_b64_e32 v[26:27], v[192:193]
	v_lshl_add_u64 v[0:1], v[44:45], 0, s[22:23]
	s_waitcnt vmcnt(3)
	s_nop 1
	v_mov_b64_e32 v[28:29], v[186:187]
	v_mov_b64_e32 v[30:31], v[188:189]
	s_waitcnt vmcnt(2)
	s_nop 1
	v_mov_b64_e32 v[32:33], v[182:183]
	v_mov_b64_e32 v[34:35], v[184:185]
	s_waitcnt vmcnt(1)
	s_nop 1
	v_mov_b64_e32 v[36:37], v[178:179]
	v_mov_b64_e32 v[38:39], v[180:181]
	v_pk_mul_f32 v[8:9], v[8:9], v[42:43] op_sel_hi:[1,0]
	v_pk_mul_f32 v[10:11], v[10:11], v[42:43] op_sel_hi:[1,0]
	v_pk_mul_f32 v[16:17], v[16:17], v[42:43] op_sel_hi:[1,0]
	v_pk_mul_f32 v[18:19], v[18:19], v[42:43] op_sel_hi:[1,0]
	v_cmp_lt_i32_e32 vcc, s31, v128
	v_accvgpr_read_b32 v4, a32
	v_accvgpr_read_b32 v0, a28
	v_accvgpr_read_b32 v5, a33
	v_accvgpr_read_b32 v6, a34
	v_accvgpr_read_b32 v7, a35
	v_accvgpr_read_b32 v1, a29
	v_accvgpr_read_b32 v2, a30
	v_accvgpr_read_b32 v3, a31
	s_or_b64 s[18:19], vcc, s[18:19]
	v_pk_mul_f32 v[8:9], v[8:9], v[12:13]
	v_pk_add_f32 v[12:13], v[20:21], 1.0 op_sel_hi:[1,0]
	v_pk_mul_f32 v[10:11], v[10:11], v[14:15]
	v_pk_add_f32 v[14:15], v[22:23], 1.0 op_sel_hi:[1,0]
	v_pk_mul_f32 v[16:17], v[16:17], v[24:25]
	v_pk_add_f32 v[20:21], v[28:29], 1.0 op_sel_hi:[1,0]
	v_pk_mul_f32 v[18:19], v[18:19], v[26:27]
	v_pk_add_f32 v[22:23], v[30:31], 1.0 op_sel_hi:[1,0]
	v_pk_fma_f32 v[8:9], v[8:9], v[12:13], v[32:33]
	v_pk_fma_f32 v[10:11], v[10:11], v[14:15], v[34:35]
	v_pk_fma_f32 v[12:13], v[16:17], v[20:21], v[36:37]
	v_pk_fma_f32 v[14:15], v[18:19], v[22:23], v[38:39]
	v_cvt_pk_bf16_f32 v8, v8, v9
	v_cvt_pk_bf16_f32 v9, v10, v11
	v_cvt_pk_bf16_f32 v10, v12, v13
	v_cvt_pk_bf16_f32 v11, v14, v15
	global_store_dwordx4 v[40:41], v[8:11], off offset:16
	s_andn2_b64 exec, exec, s[18:19]
	s_cbranch_execz .LBB0_2106
